# single-unit GEMM K-loops: loop-top vmcnt(0) drain added (mirrors the P1 loop)
# baseline (speedup 1.0000x reference)
.LBB0_518:
	ds_read_b128 v[148:151], v143
	ds_read_b128 v[152:155], v143 offset:1024
	ds_read_b128 v[158:161], v143 offset:2048
	ds_read_b128 v[162:165], v143 offset:3072
	s_waitcnt vmcnt(0)
	ds_read_b128 v[166:169], v144
	ds_read_b128 v[170:173], v144 offset:1024
	ds_read_b128 v[174:177], v144 offset:2048
	ds_read_b128 v[178:181], v144 offset:3072
	s_add_u32 s16, s8, s10
	s_addc_u32 s17, s9, s11
	s_add_u32 s16, s16, 0x1000100
	s_addc_u32 s17, s17, 0
	s_add_u32 s44, s30, s10
	s_addc_u32 s45, s31, s11
	s_cmpk_eq_i32 s10, 0x700
	s_cselect_b32 s29, s7, s17
	s_cselect_b32 s28, s6, s16
	s_cselect_b32 s17, s5, s45
	s_cselect_b32 s16, s4, s44
	s_mov_b32 m0, s34
	v_lshl_add_u64 v[214:215], v[138:139], 0, s[10:11]
	ds_read_b128 v[182:185], v145
	ds_read_b128 v[186:189], v145 offset:1024
	ds_read_b128 v[190:193], v145 offset:2048
	ds_read_b128 v[194:197], v145 offset:3072
	ds_read_b128 v[198:201], v145 offset:4096
	ds_read_b128 v[202:205], v145 offset:5120
	ds_read_b128 v[206:209], v145 offset:6144
	ds_read_b128 v[210:213], v145 offset:7168
	global_load_lds_dwordx4 v[214:215], off
	v_lshl_add_u64 v[214:215], v[140:141], 0, s[10:11]
	s_mov_b32 m0, s35
	s_nop 0
	global_load_lds_dwordx4 v[214:215], off
	s_waitcnt vmcnt(8)
	s_waitcnt lgkmcnt(0)
	s_barrier
	s_setprio 1
	s_waitcnt lgkmcnt(0)
	v_mfma_f32_16x16x32_bf16 v[126:129], v[148:151], v[182:185], v[126:129]
	v_mfma_f32_16x16x32_bf16 v[122:125], v[158:161], v[182:185], v[122:125]
	v_mfma_f32_16x16x32_bf16 v[110:113], v[148:151], v[190:193], v[110:113]
	v_mfma_f32_16x16x32_bf16 v[106:109], v[158:161], v[190:193], v[106:109]
	v_mfma_f32_16x16x32_bf16 v[94:97], v[148:151], v[198:201], v[94:97]
	v_mfma_f32_16x16x32_bf16 v[90:93], v[158:161], v[198:201], v[90:93]
	v_mfma_f32_16x16x32_bf16 v[78:81], v[148:151], v[206:209], v[78:81]
	v_mfma_f32_16x16x32_bf16 v[74:77], v[158:161], v[206:209], v[74:77]
	v_mfma_f32_16x16x32_bf16 v[126:129], v[152:155], v[186:189], v[126:129]
	v_mfma_f32_16x16x32_bf16 v[122:125], v[162:165], v[186:189], v[122:125]
	v_mfma_f32_16x16x32_bf16 v[110:113], v[152:155], v[194:197], v[110:113]
	v_mfma_f32_16x16x32_bf16 v[106:109], v[162:165], v[194:197], v[106:109]
	v_mfma_f32_16x16x32_bf16 v[94:97], v[152:155], v[202:205], v[94:97]
	v_mfma_f32_16x16x32_bf16 v[90:93], v[162:165], v[202:205], v[90:93]
	v_mfma_f32_16x16x32_bf16 v[78:81], v[152:155], v[210:213], v[78:81]
	v_mfma_f32_16x16x32_bf16 v[74:77], v[162:165], v[210:213], v[74:77]
	s_setprio 0
	s_setprio 1
	v_mfma_f32_16x16x32_bf16 v[118:121], v[166:169], v[182:185], v[118:121]
	v_mfma_f32_16x16x32_bf16 v[114:117], v[174:177], v[182:185], v[114:117]
	v_mfma_f32_16x16x32_bf16 v[102:105], v[166:169], v[190:193], v[102:105]
	v_mfma_f32_16x16x32_bf16 v[98:101], v[174:177], v[190:193], v[98:101]
	v_mfma_f32_16x16x32_bf16 v[86:89], v[166:169], v[198:201], v[86:89]
	v_mfma_f32_16x16x32_bf16 v[82:85], v[174:177], v[198:201], v[82:85]
	v_mfma_f32_16x16x32_bf16 v[70:73], v[166:169], v[206:209], v[70:73]
	v_mfma_f32_16x16x32_bf16 v[66:69], v[174:177], v[206:209], v[66:69]
	v_mfma_f32_16x16x32_bf16 v[118:121], v[170:173], v[186:189], v[118:121]
	v_mfma_f32_16x16x32_bf16 v[114:117], v[178:181], v[186:189], v[114:117]
	v_mfma_f32_16x16x32_bf16 v[102:105], v[170:173], v[194:197], v[102:105]
	v_mfma_f32_16x16x32_bf16 v[98:101], v[178:181], v[194:197], v[98:101]
	v_mfma_f32_16x16x32_bf16 v[86:89], v[170:173], v[202:205], v[86:89]
	v_mfma_f32_16x16x32_bf16 v[82:85], v[178:181], v[202:205], v[82:85]
	v_mfma_f32_16x16x32_bf16 v[70:73], v[170:173], v[210:213], v[70:73]
	v_mfma_f32_16x16x32_bf16 v[66:69], v[178:181], v[210:213], v[66:69]
	s_setprio 0
	s_barrier
	s_mov_b32 m0, s36
	v_lshl_add_u64 v[214:215], s[16:17], 0, v[132:133]
	s_add_u32 s44, s16, 0x40000
	ds_read_b128 v[182:185], v145 offset:16384
	ds_read_b128 v[186:189], v145 offset:17408
	ds_read_b128 v[190:193], v145 offset:18432
	ds_read_b128 v[194:197], v145 offset:19456
	ds_read_b128 v[198:201], v145 offset:20480
	ds_read_b128 v[202:205], v145 offset:21504
	ds_read_b128 v[206:209], v145 offset:22528
	ds_read_b128 v[210:213], v145 offset:23552
	global_load_lds_dwordx4 v132, s[16:17]
	v_lshl_add_u64 v[216:217], s[16:17], 0, v[136:137]
	s_mov_b32 m0, s37
	s_addc_u32 s45, s17, 0
	global_load_lds_dwordx4 v136, s[16:17]
	s_mov_b32 m0, s38
	v_lshl_add_u64 v[220:221], s[28:29], 0, v[134:135]
	global_load_lds_dwordx4 v132, s[44:45]
	s_mov_b32 m0, s39
	s_nop 0
	global_load_lds_dwordx4 v136, s[44:45]
	v_lshl_add_u64 v[218:219], s[28:29], 0, v[130:131]
	s_mov_b32 m0, s1
	s_nop 0
	global_load_lds_dwordx4 v130, s[28:29]
	s_mov_b32 m0, s15
	s_nop 0
	global_load_lds_dwordx4 v134, s[28:29]
	s_waitcnt vmcnt(8)
	s_waitcnt lgkmcnt(0)
	s_barrier
	s_setprio 1
	s_waitcnt lgkmcnt(0)
	v_mfma_f32_16x16x32_bf16 v[62:65], v[148:151], v[182:185], v[62:65]
	v_mfma_f32_16x16x32_bf16 v[58:61], v[158:161], v[182:185], v[58:61]
	v_mfma_f32_16x16x32_bf16 v[46:49], v[148:151], v[190:193], v[46:49]
	v_mfma_f32_16x16x32_bf16 v[42:45], v[158:161], v[190:193], v[42:45]
	v_mfma_f32_16x16x32_bf16 v[30:33], v[148:151], v[198:201], v[30:33]
	v_mfma_f32_16x16x32_bf16 v[26:29], v[158:161], v[198:201], v[26:29]
	v_mfma_f32_16x16x32_bf16 v[14:17], v[148:151], v[206:209], v[14:17]
	v_mfma_f32_16x16x32_bf16 v[10:13], v[158:161], v[206:209], v[10:13]
	v_mfma_f32_16x16x32_bf16 v[62:65], v[152:155], v[186:189], v[62:65]
	v_mfma_f32_16x16x32_bf16 v[58:61], v[162:165], v[186:189], v[58:61]
	v_mfma_f32_16x16x32_bf16 v[46:49], v[152:155], v[194:197], v[46:49]
	v_mfma_f32_16x16x32_bf16 v[42:45], v[162:165], v[194:197], v[42:45]
	v_mfma_f32_16x16x32_bf16 v[30:33], v[152:155], v[202:205], v[30:33]
	v_mfma_f32_16x16x32_bf16 v[26:29], v[162:165], v[202:205], v[26:29]
	v_mfma_f32_16x16x32_bf16 v[14:17], v[152:155], v[210:213], v[14:17]
	v_mfma_f32_16x16x32_bf16 v[10:13], v[162:165], v[210:213], v[10:13]
	s_setprio 0
	s_setprio 1
	v_mfma_f32_16x16x32_bf16 v[54:57], v[166:169], v[182:185], v[54:57]
	v_mfma_f32_16x16x32_bf16 v[50:53], v[174:177], v[182:185], v[50:53]
	v_mfma_f32_16x16x32_bf16 v[38:41], v[166:169], v[190:193], v[38:41]
	v_mfma_f32_16x16x32_bf16 v[34:37], v[174:177], v[190:193], v[34:37]
	v_mfma_f32_16x16x32_bf16 v[22:25], v[166:169], v[198:201], v[22:25]
	v_mfma_f32_16x16x32_bf16 v[18:21], v[174:177], v[198:201], v[18:21]
	v_mfma_f32_16x16x32_bf16 v[6:9], v[166:169], v[206:209], v[6:9]
	v_mfma_f32_16x16x32_bf16 v[2:5], v[174:177], v[206:209], v[2:5]
	v_mfma_f32_16x16x32_bf16 v[54:57], v[170:173], v[186:189], v[54:57]
	v_mfma_f32_16x16x32_bf16 v[50:53], v[178:181], v[186:189], v[50:53]
	v_mfma_f32_16x16x32_bf16 v[38:41], v[170:173], v[194:197], v[38:41]
	v_mfma_f32_16x16x32_bf16 v[34:37], v[178:181], v[194:197], v[34:37]
	v_mfma_f32_16x16x32_bf16 v[22:25], v[170:173], v[202:205], v[22:25]
	v_mfma_f32_16x16x32_bf16 v[18:21], v[178:181], v[202:205], v[18:21]
	v_mfma_f32_16x16x32_bf16 v[6:9], v[170:173], v[210:213], v[6:9]
	v_mfma_f32_16x16x32_bf16 v[2:5], v[178:181], v[210:213], v[2:5]
	s_setprio 0
	s_barrier
	ds_read_b128 v[148:151], v146
	ds_read_b128 v[152:155], v146 offset:1024
	ds_read_b128 v[158:161], v146 offset:2048
	ds_read_b128 v[162:165], v146 offset:3072
	ds_read_b128 v[166:169], v147
	ds_read_b128 v[170:173], v147 offset:1024
	ds_read_b128 v[174:177], v147 offset:2048
	ds_read_b128 v[178:181], v147 offset:3072
	s_add_u32 s28, s28, 0x40000
	s_addc_u32 s29, s29, 0
	s_mov_b32 m0, s20
	ds_read_b128 v[182:185], v145 offset:32768
	ds_read_b128 v[186:189], v145 offset:33792
	ds_read_b128 v[190:193], v145 offset:34816
	ds_read_b128 v[194:197], v145 offset:35840
	ds_read_b128 v[198:201], v145 offset:36864
	ds_read_b128 v[202:205], v145 offset:37888
	ds_read_b128 v[206:209], v145 offset:38912
	ds_read_b128 v[210:213], v145 offset:39936
	global_load_lds_dwordx4 v130, s[28:29]
	s_mov_b32 m0, s21
	s_nop 0
	global_load_lds_dwordx4 v134, s[28:29]
	s_waitcnt vmcnt(8)
	s_waitcnt lgkmcnt(0)
	s_barrier
	s_setprio 1
	s_waitcnt lgkmcnt(0)
	v_mfma_f32_16x16x32_bf16 v[126:129], v[148:151], v[182:185], v[126:129]
	v_mfma_f32_16x16x32_bf16 v[122:125], v[158:161], v[182:185], v[122:125]
	v_mfma_f32_16x16x32_bf16 v[110:113], v[148:151], v[190:193], v[110:113]
	v_mfma_f32_16x16x32_bf16 v[106:109], v[158:161], v[190:193], v[106:109]
	v_mfma_f32_16x16x32_bf16 v[94:97], v[148:151], v[198:201], v[94:97]
	v_mfma_f32_16x16x32_bf16 v[90:93], v[158:161], v[198:201], v[90:93]
	v_mfma_f32_16x16x32_bf16 v[78:81], v[148:151], v[206:209], v[78:81]
	v_mfma_f32_16x16x32_bf16 v[74:77], v[158:161], v[206:209], v[74:77]
	v_mfma_f32_16x16x32_bf16 v[126:129], v[152:155], v[186:189], v[126:129]
	v_mfma_f32_16x16x32_bf16 v[122:125], v[162:165], v[186:189], v[122:125]
	v_mfma_f32_16x16x32_bf16 v[110:113], v[152:155], v[194:197], v[110:113]
	v_mfma_f32_16x16x32_bf16 v[106:109], v[162:165], v[194:197], v[106:109]
	v_mfma_f32_16x16x32_bf16 v[94:97], v[152:155], v[202:205], v[94:97]
	v_mfma_f32_16x16x32_bf16 v[90:93], v[162:165], v[202:205], v[90:93]
	v_mfma_f32_16x16x32_bf16 v[78:81], v[152:155], v[210:213], v[78:81]
	v_mfma_f32_16x16x32_bf16 v[74:77], v[162:165], v[210:213], v[74:77]
	s_setprio 0
	s_setprio 1
	v_mfma_f32_16x16x32_bf16 v[118:121], v[166:169], v[182:185], v[118:121]
	v_mfma_f32_16x16x32_bf16 v[114:117], v[174:177], v[182:185], v[114:117]
	v_mfma_f32_16x16x32_bf16 v[102:105], v[166:169], v[190:193], v[102:105]
	v_mfma_f32_16x16x32_bf16 v[98:101], v[174:177], v[190:193], v[98:101]
	v_mfma_f32_16x16x32_bf16 v[86:89], v[166:169], v[198:201], v[86:89]
	v_mfma_f32_16x16x32_bf16 v[82:85], v[174:177], v[198:201], v[82:85]
	v_mfma_f32_16x16x32_bf16 v[70:73], v[166:169], v[206:209], v[70:73]
	v_mfma_f32_16x16x32_bf16 v[66:69], v[174:177], v[206:209], v[66:69]
	v_mfma_f32_16x16x32_bf16 v[118:121], v[170:173], v[186:189], v[118:121]
	v_mfma_f32_16x16x32_bf16 v[114:117], v[178:181], v[186:189], v[114:117]
	v_mfma_f32_16x16x32_bf16 v[102:105], v[170:173], v[194:197], v[102:105]
	v_mfma_f32_16x16x32_bf16 v[98:101], v[178:181], v[194:197], v[98:101]
	v_mfma_f32_16x16x32_bf16 v[86:89], v[170:173], v[202:205], v[86:89]
	v_mfma_f32_16x16x32_bf16 v[82:85], v[178:181], v[202:205], v[82:85]
	v_mfma_f32_16x16x32_bf16 v[70:73], v[170:173], v[210:213], v[70:73]
	v_mfma_f32_16x16x32_bf16 v[66:69], v[178:181], v[210:213], v[66:69]
	s_setprio 0
	s_barrier
	s_mov_b32 m0, s40
	v_lshl_add_u64 v[214:215], v[214:215], 0, s[2:3]
	s_add_u32 s16, s16, 0x40080
	ds_read_b128 v[182:185], v145 offset:49152
	ds_read_b128 v[186:189], v145 offset:50176
	ds_read_b128 v[190:193], v145 offset:51200
	ds_read_b128 v[194:197], v145 offset:52224
	ds_read_b128 v[198:201], v145 offset:53248
	ds_read_b128 v[202:205], v145 offset:54272
	ds_read_b128 v[206:209], v145 offset:55296
	ds_read_b128 v[210:213], v145 offset:56320
	global_load_lds_dwordx4 v[214:215], off
	v_lshl_add_u64 v[214:215], v[216:217], 0, s[2:3]
	s_mov_b32 m0, s41
	s_addc_u32 s17, s17, 0
	global_load_lds_dwordx4 v[214:215], off
	s_mov_b32 m0, s42
	s_nop 0
	global_load_lds_dwordx4 v132, s[16:17]
	s_mov_b32 m0, s43
	s_nop 0
	global_load_lds_dwordx4 v136, s[16:17]
	v_lshl_add_u64 v[214:215], v[218:219], 0, s[2:3]
	s_mov_b32 m0, s22
	s_nop 0
	global_load_lds_dwordx4 v[214:215], off
	v_lshl_add_u64 v[214:215], v[220:221], 0, s[2:3]
	s_mov_b32 m0, s23
	s_nop 0
	global_load_lds_dwordx4 v[214:215], off
	s_waitcnt vmcnt(8)
	s_waitcnt lgkmcnt(0)
	s_barrier
	s_setprio 1
	s_waitcnt lgkmcnt(0)
	v_mfma_f32_16x16x32_bf16 v[62:65], v[148:151], v[182:185], v[62:65]
	v_mfma_f32_16x16x32_bf16 v[58:61], v[158:161], v[182:185], v[58:61]
	v_mfma_f32_16x16x32_bf16 v[46:49], v[148:151], v[190:193], v[46:49]
	v_mfma_f32_16x16x32_bf16 v[42:45], v[158:161], v[190:193], v[42:45]
	v_mfma_f32_16x16x32_bf16 v[30:33], v[148:151], v[198:201], v[30:33]
	v_mfma_f32_16x16x32_bf16 v[26:29], v[158:161], v[198:201], v[26:29]
	v_mfma_f32_16x16x32_bf16 v[14:17], v[148:151], v[206:209], v[14:17]
	v_mfma_f32_16x16x32_bf16 v[10:13], v[158:161], v[206:209], v[10:13]
	v_mfma_f32_16x16x32_bf16 v[62:65], v[152:155], v[186:189], v[62:65]
	v_mfma_f32_16x16x32_bf16 v[58:61], v[162:165], v[186:189], v[58:61]
	v_mfma_f32_16x16x32_bf16 v[46:49], v[152:155], v[194:197], v[46:49]
	v_mfma_f32_16x16x32_bf16 v[42:45], v[162:165], v[194:197], v[42:45]
	v_mfma_f32_16x16x32_bf16 v[30:33], v[152:155], v[202:205], v[30:33]
	v_mfma_f32_16x16x32_bf16 v[26:29], v[162:165], v[202:205], v[26:29]
	v_mfma_f32_16x16x32_bf16 v[14:17], v[152:155], v[210:213], v[14:17]
	v_mfma_f32_16x16x32_bf16 v[10:13], v[162:165], v[210:213], v[10:13]
	s_setprio 0
	s_setprio 1
	v_mfma_f32_16x16x32_bf16 v[54:57], v[166:169], v[182:185], v[54:57]
	v_mfma_f32_16x16x32_bf16 v[50:53], v[174:177], v[182:185], v[50:53]
	v_mfma_f32_16x16x32_bf16 v[38:41], v[166:169], v[190:193], v[38:41]
	v_mfma_f32_16x16x32_bf16 v[34:37], v[174:177], v[190:193], v[34:37]
	v_mfma_f32_16x16x32_bf16 v[22:25], v[166:169], v[198:201], v[22:25]
	v_mfma_f32_16x16x32_bf16 v[18:21], v[174:177], v[198:201], v[18:21]
	v_mfma_f32_16x16x32_bf16 v[6:9], v[166:169], v[206:209], v[6:9]
	v_mfma_f32_16x16x32_bf16 v[2:5], v[174:177], v[206:209], v[2:5]
	v_mfma_f32_16x16x32_bf16 v[54:57], v[170:173], v[186:189], v[54:57]
	v_mfma_f32_16x16x32_bf16 v[50:53], v[178:181], v[186:189], v[50:53]
	v_mfma_f32_16x16x32_bf16 v[38:41], v[170:173], v[194:197], v[38:41]
	v_mfma_f32_16x16x32_bf16 v[34:37], v[178:181], v[194:197], v[34:37]
	v_mfma_f32_16x16x32_bf16 v[22:25], v[170:173], v[202:205], v[22:25]
	v_mfma_f32_16x16x32_bf16 v[18:21], v[178:181], v[202:205], v[18:21]
	v_mfma_f32_16x16x32_bf16 v[6:9], v[170:173], v[210:213], v[6:9]
	v_mfma_f32_16x16x32_bf16 v[2:5], v[178:181], v[210:213], v[2:5]
	s_setprio 0
	s_barrier
	s_add_i32 s33, s33, 2
	s_add_u32 s10, s10, 0x100
	s_addc_u32 s11, s11, 0
	s_cmp_gt_u32 s33, 13
	s_cbranch_scc0 .LBB0_518
	s_cmpk_lt_u32 s14, 0x100
	s_cbranch_scc0 .LBB0_521
	s_barrier

.LBB0_1250:
	ds_read_b128 v[146:149], v140
	ds_read_b128 v[150:153], v140 offset:1024
	ds_read_b128 v[154:157], v140 offset:2048
	ds_read_b128 v[158:161], v140 offset:3072
	s_waitcnt vmcnt(0)
	ds_read_b128 v[162:165], v141
	ds_read_b128 v[166:169], v141 offset:1024
	ds_read_b128 v[170:173], v141 offset:2048
	ds_read_b128 v[174:177], v141 offset:3072
	s_add_u32 s14, s10, s12
	s_addc_u32 s15, s11, s13
	s_add_u32 s14, s14, 0x11400100
	s_addc_u32 s15, s15, 0
	s_add_u32 s39, s1, s12
	s_addc_u32 s40, s26, s13
	s_cmpk_eq_i32 s12, 0x700
	s_cselect_b32 s17, s9, s15
	s_cselect_b32 s16, s8, s14
	s_cselect_b32 s15, s7, s40
	s_cselect_b32 s14, s6, s39
	s_mov_b32 m0, s28
	v_lshl_add_u64 v[210:211], v[134:135], 0, s[12:13]
	ds_read_b128 v[178:181], v142
	ds_read_b128 v[182:185], v142 offset:1024
	ds_read_b128 v[186:189], v142 offset:2048
	ds_read_b128 v[190:193], v142 offset:3072
	ds_read_b128 v[194:197], v142 offset:4096
	ds_read_b128 v[198:201], v142 offset:5120
	ds_read_b128 v[202:205], v142 offset:6144
	ds_read_b128 v[206:209], v142 offset:7168
	global_load_lds_dwordx4 v[210:211], off
	v_lshl_add_u64 v[210:211], v[136:137], 0, s[12:13]
	s_mov_b32 m0, s29
	s_nop 0
	global_load_lds_dwordx4 v[210:211], off
	s_waitcnt vmcnt(8)
	s_waitcnt lgkmcnt(0)
	s_barrier
	s_setprio 1
	s_waitcnt lgkmcnt(0)
	v_mfma_f32_16x16x32_bf16 v[126:129], v[146:149], v[178:181], v[126:129]
	v_mfma_f32_16x16x32_bf16 v[122:125], v[154:157], v[178:181], v[122:125]
	v_mfma_f32_16x16x32_bf16 v[118:121], v[146:149], v[186:189], v[118:121]
	v_mfma_f32_16x16x32_bf16 v[114:117], v[154:157], v[186:189], v[114:117]
	v_mfma_f32_16x16x32_bf16 v[106:109], v[146:149], v[194:197], v[106:109]
	v_mfma_f32_16x16x32_bf16 v[98:101], v[154:157], v[194:197], v[98:101]
	v_mfma_f32_16x16x32_bf16 v[82:85], v[146:149], v[202:205], v[82:85]
	v_mfma_f32_16x16x32_bf16 v[74:77], v[154:157], v[202:205], v[74:77]
	v_mfma_f32_16x16x32_bf16 v[126:129], v[150:153], v[182:185], v[126:129]
	v_mfma_f32_16x16x32_bf16 v[122:125], v[158:161], v[182:185], v[122:125]
	v_mfma_f32_16x16x32_bf16 v[118:121], v[150:153], v[190:193], v[118:121]
	v_mfma_f32_16x16x32_bf16 v[114:117], v[158:161], v[190:193], v[114:117]
	v_mfma_f32_16x16x32_bf16 v[106:109], v[150:153], v[198:201], v[106:109]
	v_mfma_f32_16x16x32_bf16 v[98:101], v[158:161], v[198:201], v[98:101]
	v_mfma_f32_16x16x32_bf16 v[82:85], v[150:153], v[206:209], v[82:85]
	v_mfma_f32_16x16x32_bf16 v[74:77], v[158:161], v[206:209], v[74:77]
	s_setprio 0
	s_setprio 1
	v_mfma_f32_16x16x32_bf16 v[110:113], v[162:165], v[178:181], v[110:113]
	v_mfma_f32_16x16x32_bf16 v[102:105], v[170:173], v[178:181], v[102:105]
	v_mfma_f32_16x16x32_bf16 v[94:97], v[162:165], v[186:189], v[94:97]
	v_mfma_f32_16x16x32_bf16 v[90:93], v[170:173], v[186:189], v[90:93]
	v_mfma_f32_16x16x32_bf16 v[86:89], v[162:165], v[194:197], v[86:89]
	v_mfma_f32_16x16x32_bf16 v[78:81], v[170:173], v[194:197], v[78:81]
	v_mfma_f32_16x16x32_bf16 v[70:73], v[162:165], v[202:205], v[70:73]
	v_mfma_f32_16x16x32_bf16 v[66:69], v[170:173], v[202:205], v[66:69]
	v_mfma_f32_16x16x32_bf16 v[110:113], v[166:169], v[182:185], v[110:113]
	v_mfma_f32_16x16x32_bf16 v[102:105], v[174:177], v[182:185], v[102:105]
	v_mfma_f32_16x16x32_bf16 v[94:97], v[166:169], v[190:193], v[94:97]
	v_mfma_f32_16x16x32_bf16 v[90:93], v[174:177], v[190:193], v[90:93]
	v_mfma_f32_16x16x32_bf16 v[86:89], v[166:169], v[198:201], v[86:89]
	v_mfma_f32_16x16x32_bf16 v[78:81], v[174:177], v[198:201], v[78:81]
	v_mfma_f32_16x16x32_bf16 v[70:73], v[166:169], v[206:209], v[70:73]
	v_mfma_f32_16x16x32_bf16 v[66:69], v[174:177], v[206:209], v[66:69]
	s_setprio 0
	s_barrier
	s_mov_b32 m0, s30
	v_lshl_add_u64 v[210:211], s[14:15], 0, v[130:131]
	s_add_u32 s40, s14, 0x40000
	ds_read_b128 v[178:181], v142 offset:16384
	ds_read_b128 v[182:185], v142 offset:17408
	ds_read_b128 v[186:189], v142 offset:18432
	ds_read_b128 v[190:193], v142 offset:19456
	ds_read_b128 v[194:197], v142 offset:20480
	ds_read_b128 v[198:201], v142 offset:21504
	ds_read_b128 v[202:205], v142 offset:22528
	ds_read_b128 v[206:209], v142 offset:23552
	global_load_lds_dwordx4 v130, s[14:15]
	v_lshl_add_u64 v[212:213], s[14:15], 0, v[132:133]
	s_mov_b32 m0, s31
	s_addc_u32 s41, s15, 0
	global_load_lds_dwordx4 v132, s[14:15]
	s_mov_b32 m0, s33
	v_lshl_add_u64 v[216:217], s[16:17], 0, v[132:133]
	global_load_lds_dwordx4 v130, s[40:41]
	s_mov_b32 m0, s34
	s_nop 0
	global_load_lds_dwordx4 v132, s[40:41]
	v_lshl_add_u64 v[214:215], s[16:17], 0, v[130:131]
	s_mov_b32 m0, s5
	s_nop 0
	global_load_lds_dwordx4 v130, s[16:17]
	s_mov_b32 m0, s21
	s_nop 0
	global_load_lds_dwordx4 v132, s[16:17]
	s_waitcnt vmcnt(8)
	s_waitcnt lgkmcnt(0)
	s_barrier
	s_setprio 1
	s_waitcnt lgkmcnt(0)
	v_mfma_f32_16x16x32_bf16 v[62:65], v[146:149], v[178:181], v[62:65]
	v_mfma_f32_16x16x32_bf16 v[58:61], v[154:157], v[178:181], v[58:61]
	v_mfma_f32_16x16x32_bf16 v[54:57], v[146:149], v[186:189], v[54:57]
	v_mfma_f32_16x16x32_bf16 v[50:53], v[154:157], v[186:189], v[50:53]
	v_mfma_f32_16x16x32_bf16 v[34:37], v[146:149], v[194:197], v[34:37]
	v_mfma_f32_16x16x32_bf16 v[26:29], v[154:157], v[194:197], v[26:29]
	v_mfma_f32_16x16x32_bf16 v[22:25], v[146:149], v[202:205], v[22:25]
	v_mfma_f32_16x16x32_bf16 v[10:13], v[154:157], v[202:205], v[10:13]
	v_mfma_f32_16x16x32_bf16 v[62:65], v[150:153], v[182:185], v[62:65]
	v_mfma_f32_16x16x32_bf16 v[58:61], v[158:161], v[182:185], v[58:61]
	v_mfma_f32_16x16x32_bf16 v[54:57], v[150:153], v[190:193], v[54:57]
	v_mfma_f32_16x16x32_bf16 v[50:53], v[158:161], v[190:193], v[50:53]
	v_mfma_f32_16x16x32_bf16 v[34:37], v[150:153], v[198:201], v[34:37]
	v_mfma_f32_16x16x32_bf16 v[26:29], v[158:161], v[198:201], v[26:29]
	v_mfma_f32_16x16x32_bf16 v[22:25], v[150:153], v[206:209], v[22:25]
	v_mfma_f32_16x16x32_bf16 v[10:13], v[158:161], v[206:209], v[10:13]
	s_setprio 0
	s_setprio 1
	v_mfma_f32_16x16x32_bf16 v[46:49], v[162:165], v[178:181], v[46:49]
	v_mfma_f32_16x16x32_bf16 v[42:45], v[170:173], v[178:181], v[42:45]
	v_mfma_f32_16x16x32_bf16 v[38:41], v[162:165], v[186:189], v[38:41]
	v_mfma_f32_16x16x32_bf16 v[30:33], v[170:173], v[186:189], v[30:33]
	v_mfma_f32_16x16x32_bf16 v[18:21], v[162:165], v[194:197], v[18:21]
	v_mfma_f32_16x16x32_bf16 v[14:17], v[170:173], v[194:197], v[14:17]
	v_mfma_f32_16x16x32_bf16 v[6:9], v[162:165], v[202:205], v[6:9]
	v_mfma_f32_16x16x32_bf16 v[2:5], v[170:173], v[202:205], v[2:5]
	v_mfma_f32_16x16x32_bf16 v[46:49], v[166:169], v[182:185], v[46:49]
	v_mfma_f32_16x16x32_bf16 v[42:45], v[174:177], v[182:185], v[42:45]
	v_mfma_f32_16x16x32_bf16 v[38:41], v[166:169], v[190:193], v[38:41]
	v_mfma_f32_16x16x32_bf16 v[30:33], v[174:177], v[190:193], v[30:33]
	v_mfma_f32_16x16x32_bf16 v[18:21], v[166:169], v[198:201], v[18:21]
	v_mfma_f32_16x16x32_bf16 v[14:17], v[174:177], v[198:201], v[14:17]
	v_mfma_f32_16x16x32_bf16 v[6:9], v[166:169], v[206:209], v[6:9]
	v_mfma_f32_16x16x32_bf16 v[2:5], v[174:177], v[206:209], v[2:5]
	s_setprio 0
	s_barrier
	ds_read_b128 v[146:149], v143
	ds_read_b128 v[150:153], v143 offset:1024
	ds_read_b128 v[154:157], v143 offset:2048
	ds_read_b128 v[158:161], v143 offset:3072
	ds_read_b128 v[162:165], v144
	ds_read_b128 v[166:169], v144 offset:1024
	ds_read_b128 v[170:173], v144 offset:2048
	ds_read_b128 v[174:177], v144 offset:3072
	s_add_u32 s16, s16, 0x40000
	s_addc_u32 s17, s17, 0
	s_mov_b32 m0, s22
	ds_read_b128 v[178:181], v142 offset:32768
	ds_read_b128 v[182:185], v142 offset:33792
	ds_read_b128 v[186:189], v142 offset:34816
	ds_read_b128 v[190:193], v142 offset:35840
	ds_read_b128 v[194:197], v142 offset:36864
	ds_read_b128 v[198:201], v142 offset:37888
	ds_read_b128 v[202:205], v142 offset:38912
	ds_read_b128 v[206:209], v142 offset:39936
	global_load_lds_dwordx4 v130, s[16:17]
	s_mov_b32 m0, s23
	s_nop 0
	global_load_lds_dwordx4 v132, s[16:17]
	s_waitcnt vmcnt(8)
	s_waitcnt lgkmcnt(0)
	s_barrier
	s_setprio 1
	s_waitcnt lgkmcnt(0)
	v_mfma_f32_16x16x32_bf16 v[126:129], v[146:149], v[178:181], v[126:129]
	v_mfma_f32_16x16x32_bf16 v[122:125], v[154:157], v[178:181], v[122:125]
	v_mfma_f32_16x16x32_bf16 v[118:121], v[146:149], v[186:189], v[118:121]
	v_mfma_f32_16x16x32_bf16 v[114:117], v[154:157], v[186:189], v[114:117]
	v_mfma_f32_16x16x32_bf16 v[106:109], v[146:149], v[194:197], v[106:109]
	v_mfma_f32_16x16x32_bf16 v[98:101], v[154:157], v[194:197], v[98:101]
	v_mfma_f32_16x16x32_bf16 v[82:85], v[146:149], v[202:205], v[82:85]
	v_mfma_f32_16x16x32_bf16 v[74:77], v[154:157], v[202:205], v[74:77]
	v_mfma_f32_16x16x32_bf16 v[126:129], v[150:153], v[182:185], v[126:129]
	v_mfma_f32_16x16x32_bf16 v[122:125], v[158:161], v[182:185], v[122:125]
	v_mfma_f32_16x16x32_bf16 v[118:121], v[150:153], v[190:193], v[118:121]
	v_mfma_f32_16x16x32_bf16 v[114:117], v[158:161], v[190:193], v[114:117]
	v_mfma_f32_16x16x32_bf16 v[106:109], v[150:153], v[198:201], v[106:109]
	v_mfma_f32_16x16x32_bf16 v[98:101], v[158:161], v[198:201], v[98:101]
	v_mfma_f32_16x16x32_bf16 v[82:85], v[150:153], v[206:209], v[82:85]
	v_mfma_f32_16x16x32_bf16 v[74:77], v[158:161], v[206:209], v[74:77]
	s_setprio 0
	s_setprio 1
	v_mfma_f32_16x16x32_bf16 v[110:113], v[162:165], v[178:181], v[110:113]
	v_mfma_f32_16x16x32_bf16 v[102:105], v[170:173], v[178:181], v[102:105]
	v_mfma_f32_16x16x32_bf16 v[94:97], v[162:165], v[186:189], v[94:97]
	v_mfma_f32_16x16x32_bf16 v[90:93], v[170:173], v[186:189], v[90:93]
	v_mfma_f32_16x16x32_bf16 v[86:89], v[162:165], v[194:197], v[86:89]
	v_mfma_f32_16x16x32_bf16 v[78:81], v[170:173], v[194:197], v[78:81]
	v_mfma_f32_16x16x32_bf16 v[70:73], v[162:165], v[202:205], v[70:73]
	v_mfma_f32_16x16x32_bf16 v[66:69], v[170:173], v[202:205], v[66:69]
	v_mfma_f32_16x16x32_bf16 v[110:113], v[166:169], v[182:185], v[110:113]
	v_mfma_f32_16x16x32_bf16 v[102:105], v[174:177], v[182:185], v[102:105]
	v_mfma_f32_16x16x32_bf16 v[94:97], v[166:169], v[190:193], v[94:97]
	v_mfma_f32_16x16x32_bf16 v[90:93], v[174:177], v[190:193], v[90:93]
	v_mfma_f32_16x16x32_bf16 v[86:89], v[166:169], v[198:201], v[86:89]
	v_mfma_f32_16x16x32_bf16 v[78:81], v[174:177], v[198:201], v[78:81]
	v_mfma_f32_16x16x32_bf16 v[70:73], v[166:169], v[206:209], v[70:73]
	v_mfma_f32_16x16x32_bf16 v[66:69], v[174:177], v[206:209], v[66:69]
	s_setprio 0
	s_barrier
	s_mov_b32 m0, s35
	v_lshl_add_u64 v[210:211], v[210:211], 0, s[2:3]
	s_add_u32 s14, s14, 0x40080
	ds_read_b128 v[178:181], v142 offset:49152
	ds_read_b128 v[182:185], v142 offset:50176
	ds_read_b128 v[186:189], v142 offset:51200
	ds_read_b128 v[190:193], v142 offset:52224
	ds_read_b128 v[194:197], v142 offset:53248
	ds_read_b128 v[198:201], v142 offset:54272
	ds_read_b128 v[202:205], v142 offset:55296
	ds_read_b128 v[206:209], v142 offset:56320
	global_load_lds_dwordx4 v[210:211], off
	v_lshl_add_u64 v[210:211], v[212:213], 0, s[2:3]
	s_mov_b32 m0, s36
	s_addc_u32 s15, s15, 0
	global_load_lds_dwordx4 v[210:211], off
	s_mov_b32 m0, s37
	s_nop 0
	global_load_lds_dwordx4 v130, s[14:15]
	s_mov_b32 m0, s38
	s_nop 0
	global_load_lds_dwordx4 v132, s[14:15]
	v_lshl_add_u64 v[210:211], v[214:215], 0, s[2:3]
	s_mov_b32 m0, s24
	s_nop 0
	global_load_lds_dwordx4 v[210:211], off
	v_lshl_add_u64 v[210:211], v[216:217], 0, s[2:3]
	s_mov_b32 m0, s25
	s_nop 0
	global_load_lds_dwordx4 v[210:211], off
	s_waitcnt vmcnt(8)
	s_waitcnt lgkmcnt(0)
	s_barrier
	s_setprio 1
	s_waitcnt lgkmcnt(0)
	v_mfma_f32_16x16x32_bf16 v[62:65], v[146:149], v[178:181], v[62:65]
	v_mfma_f32_16x16x32_bf16 v[58:61], v[154:157], v[178:181], v[58:61]
	v_mfma_f32_16x16x32_bf16 v[54:57], v[146:149], v[186:189], v[54:57]
	v_mfma_f32_16x16x32_bf16 v[50:53], v[154:157], v[186:189], v[50:53]
	v_mfma_f32_16x16x32_bf16 v[34:37], v[146:149], v[194:197], v[34:37]
	v_mfma_f32_16x16x32_bf16 v[26:29], v[154:157], v[194:197], v[26:29]
	v_mfma_f32_16x16x32_bf16 v[22:25], v[146:149], v[202:205], v[22:25]
	v_mfma_f32_16x16x32_bf16 v[10:13], v[154:157], v[202:205], v[10:13]
	v_mfma_f32_16x16x32_bf16 v[62:65], v[150:153], v[182:185], v[62:65]
	v_mfma_f32_16x16x32_bf16 v[58:61], v[158:161], v[182:185], v[58:61]
	v_mfma_f32_16x16x32_bf16 v[54:57], v[150:153], v[190:193], v[54:57]
	v_mfma_f32_16x16x32_bf16 v[50:53], v[158:161], v[190:193], v[50:53]
	v_mfma_f32_16x16x32_bf16 v[34:37], v[150:153], v[198:201], v[34:37]
	v_mfma_f32_16x16x32_bf16 v[26:29], v[158:161], v[198:201], v[26:29]
	v_mfma_f32_16x16x32_bf16 v[22:25], v[150:153], v[206:209], v[22:25]
	v_mfma_f32_16x16x32_bf16 v[10:13], v[158:161], v[206:209], v[10:13]
	s_setprio 0
	s_setprio 1
	v_mfma_f32_16x16x32_bf16 v[46:49], v[162:165], v[178:181], v[46:49]
	v_mfma_f32_16x16x32_bf16 v[42:45], v[170:173], v[178:181], v[42:45]
	v_mfma_f32_16x16x32_bf16 v[38:41], v[162:165], v[186:189], v[38:41]
	v_mfma_f32_16x16x32_bf16 v[30:33], v[170:173], v[186:189], v[30:33]
	v_mfma_f32_16x16x32_bf16 v[18:21], v[162:165], v[194:197], v[18:21]
	v_mfma_f32_16x16x32_bf16 v[14:17], v[170:173], v[194:197], v[14:17]
	v_mfma_f32_16x16x32_bf16 v[6:9], v[162:165], v[202:205], v[6:9]
	v_mfma_f32_16x16x32_bf16 v[2:5], v[170:173], v[202:205], v[2:5]
	v_mfma_f32_16x16x32_bf16 v[46:49], v[166:169], v[182:185], v[46:49]
	v_mfma_f32_16x16x32_bf16 v[42:45], v[174:177], v[182:185], v[42:45]
	v_mfma_f32_16x16x32_bf16 v[38:41], v[166:169], v[190:193], v[38:41]
	v_mfma_f32_16x16x32_bf16 v[30:33], v[174:177], v[190:193], v[30:33]
	v_mfma_f32_16x16x32_bf16 v[18:21], v[166:169], v[198:201], v[18:21]
	v_mfma_f32_16x16x32_bf16 v[14:17], v[174:177], v[198:201], v[14:17]
	v_mfma_f32_16x16x32_bf16 v[6:9], v[166:169], v[206:209], v[6:9]
	v_mfma_f32_16x16x32_bf16 v[2:5], v[174:177], v[206:209], v[2:5]
	s_setprio 0
	s_barrier
	s_add_i32 s27, s27, 2
	s_add_u32 s12, s12, 0x100
	s_addc_u32 s13, s13, 0
	s_cmp_gt_u32 s27, 13
	s_cbranch_scc0 .LBB0_1250
	s_cmpk_lt_u32 s19, 0x100
	s_cbranch_scc0 .LBB0_1253
	s_barrier

.LBB0_1381:
	ds_read_b128 v[138:141], v147
	ds_read_b128 v[150:153], v147 offset:1024
	ds_read_b128 v[154:157], v147 offset:2048
	ds_read_b128 v[158:161], v147 offset:3072
	s_waitcnt vmcnt(0)
	ds_read_b128 v[162:165], v148
	ds_read_b128 v[166:169], v148 offset:1024
	ds_read_b128 v[170:173], v148 offset:2048
	ds_read_b128 v[174:177], v148 offset:3072
	s_add_u32 s24, s2, 0xfffc0080
	s_addc_u32 s25, s3, -1
	s_cmp_eq_u32 s53, 12
	s_cselect_b32 s27, s17, s25
	s_cselect_b32 s26, s49, s24
	s_cselect_b32 s25, s15, s52
	s_cselect_b32 s24, s50, s51
	s_add_i32 m0, s23, 0xc000
	ds_read_b128 v[178:181], v149
	ds_read_b128 v[182:185], v149 offset:1024
	ds_read_b128 v[186:189], v149 offset:2048
	ds_read_b128 v[190:193], v149 offset:3072
	ds_read_b128 v[194:197], v149 offset:4096
	ds_read_b128 v[198:201], v149 offset:5120
	ds_read_b128 v[202:205], v149 offset:6144
	ds_read_b128 v[206:209], v149 offset:7168
	global_load_lds_dwordx4 v132, s[2:3]
	s_add_i32 m0, s23, 0xe000
	s_nop 0
	global_load_lds_dwordx4 v134, s[2:3]
	s_waitcnt vmcnt(8)
	s_waitcnt lgkmcnt(0)
	s_barrier
	s_setprio 1
	s_waitcnt lgkmcnt(0)
	v_mfma_f32_16x16x32_bf16 v[124:127], v[138:141], v[178:181], v[124:127]
	v_mfma_f32_16x16x32_bf16 v[120:123], v[154:157], v[178:181], v[120:123]
	v_mfma_f32_16x16x32_bf16 v[116:119], v[138:141], v[186:189], v[116:119]
	v_mfma_f32_16x16x32_bf16 v[112:115], v[154:157], v[186:189], v[112:115]
	v_mfma_f32_16x16x32_bf16 v[104:107], v[138:141], v[194:197], v[104:107]
	v_mfma_f32_16x16x32_bf16 v[96:99], v[154:157], v[194:197], v[96:99]
	v_mfma_f32_16x16x32_bf16 v[88:91], v[138:141], v[202:205], v[88:91]
	v_mfma_f32_16x16x32_bf16 v[80:83], v[154:157], v[202:205], v[80:83]
	v_mfma_f32_16x16x32_bf16 v[124:127], v[150:153], v[182:185], v[124:127]
	v_mfma_f32_16x16x32_bf16 v[120:123], v[158:161], v[182:185], v[120:123]
	v_mfma_f32_16x16x32_bf16 v[116:119], v[150:153], v[190:193], v[116:119]
	v_mfma_f32_16x16x32_bf16 v[112:115], v[158:161], v[190:193], v[112:115]
	v_mfma_f32_16x16x32_bf16 v[104:107], v[150:153], v[198:201], v[104:107]
	v_mfma_f32_16x16x32_bf16 v[96:99], v[158:161], v[198:201], v[96:99]
	v_mfma_f32_16x16x32_bf16 v[88:91], v[150:153], v[206:209], v[88:91]
	v_mfma_f32_16x16x32_bf16 v[80:83], v[158:161], v[206:209], v[80:83]
	s_setprio 0
	s_setprio 1
	v_mfma_f32_16x16x32_bf16 v[108:111], v[162:165], v[178:181], v[108:111]
	v_mfma_f32_16x16x32_bf16 v[100:103], v[170:173], v[178:181], v[100:103]
	v_mfma_f32_16x16x32_bf16 v[92:95], v[162:165], v[186:189], v[92:95]
	v_mfma_f32_16x16x32_bf16 v[84:87], v[170:173], v[186:189], v[84:87]
	v_mfma_f32_16x16x32_bf16 v[76:79], v[162:165], v[194:197], v[76:79]
	v_mfma_f32_16x16x32_bf16 v[72:75], v[170:173], v[194:197], v[72:75]
	v_mfma_f32_16x16x32_bf16 v[68:71], v[162:165], v[202:205], v[68:71]
	v_mfma_f32_16x16x32_bf16 v[64:67], v[170:173], v[202:205], v[64:67]
	v_mfma_f32_16x16x32_bf16 v[108:111], v[166:169], v[182:185], v[108:111]
	v_mfma_f32_16x16x32_bf16 v[100:103], v[174:177], v[182:185], v[100:103]
	v_mfma_f32_16x16x32_bf16 v[92:95], v[166:169], v[190:193], v[92:95]
	v_mfma_f32_16x16x32_bf16 v[84:87], v[174:177], v[190:193], v[84:87]
	v_mfma_f32_16x16x32_bf16 v[76:79], v[166:169], v[198:201], v[76:79]
	v_mfma_f32_16x16x32_bf16 v[72:75], v[174:177], v[198:201], v[72:75]
	v_mfma_f32_16x16x32_bf16 v[68:71], v[166:169], v[206:209], v[68:71]
	v_mfma_f32_16x16x32_bf16 v[64:67], v[174:177], v[206:209], v[64:67]
	s_setprio 0
	s_barrier
	s_add_i32 s54, s4, s29
	s_mov_b32 m0, s54
	ds_read_b128 v[178:181], v149 offset:16384
	ds_read_b128 v[182:185], v149 offset:17408
	ds_read_b128 v[186:189], v149 offset:18432
	ds_read_b128 v[190:193], v149 offset:19456
	ds_read_b128 v[194:197], v149 offset:20480
	ds_read_b128 v[198:201], v149 offset:21504
	ds_read_b128 v[202:205], v149 offset:22528
	ds_read_b128 v[206:209], v149 offset:23552
	global_load_lds_dwordx4 v130, s[24:25]
	s_add_i32 m0, s54, 0x2000
	s_add_u32 s54, s24, 0x40000
	s_addc_u32 s55, s25, 0
	s_add_i32 s56, s41, s29
	global_load_lds_dwordx4 v128, s[24:25]
	s_mov_b32 m0, s56
	v_lshl_add_u64 v[214:215], s[26:27], 0, v[128:129]
	global_load_lds_dwordx4 v130, s[54:55]
	s_add_i32 m0, s56, 0x2000
	s_nop 0
	global_load_lds_dwordx4 v128, s[54:55]
	v_lshl_add_u64 v[212:213], s[26:27], 0, v[130:131]
	s_mov_b32 m0, s23
	s_nop 0
	global_load_lds_dwordx4 v130, s[26:27]
	s_mov_b32 m0, s34
	s_nop 0
	global_load_lds_dwordx4 v128, s[26:27]
	s_waitcnt vmcnt(8)
	s_waitcnt lgkmcnt(0)
	s_barrier
	s_setprio 1
	s_waitcnt lgkmcnt(0)
	v_mfma_f32_16x16x32_bf16 v[60:63], v[138:141], v[178:181], v[60:63]
	v_mfma_f32_16x16x32_bf16 v[56:59], v[154:157], v[178:181], v[56:59]
	v_mfma_f32_16x16x32_bf16 v[52:55], v[138:141], v[186:189], v[52:55]
	v_mfma_f32_16x16x32_bf16 v[48:51], v[154:157], v[186:189], v[48:51]
	v_mfma_f32_16x16x32_bf16 v[44:47], v[138:141], v[194:197], v[44:47]
	v_mfma_f32_16x16x32_bf16 v[32:35], v[154:157], v[194:197], v[32:35]
	v_mfma_f32_16x16x32_bf16 v[20:23], v[138:141], v[202:205], v[20:23]
	v_mfma_f32_16x16x32_bf16 v[8:11], v[154:157], v[202:205], v[8:11]
	v_mfma_f32_16x16x32_bf16 v[60:63], v[150:153], v[182:185], v[60:63]
	v_mfma_f32_16x16x32_bf16 v[56:59], v[158:161], v[182:185], v[56:59]
	v_mfma_f32_16x16x32_bf16 v[52:55], v[150:153], v[190:193], v[52:55]
	v_mfma_f32_16x16x32_bf16 v[48:51], v[158:161], v[190:193], v[48:51]
	v_mfma_f32_16x16x32_bf16 v[44:47], v[150:153], v[198:201], v[44:47]
	v_mfma_f32_16x16x32_bf16 v[32:35], v[158:161], v[198:201], v[32:35]
	v_mfma_f32_16x16x32_bf16 v[20:23], v[150:153], v[206:209], v[20:23]
	v_mfma_f32_16x16x32_bf16 v[8:11], v[158:161], v[206:209], v[8:11]
	s_setprio 0
	s_setprio 1
	v_mfma_f32_16x16x32_bf16 v[40:43], v[162:165], v[178:181], v[40:43]
	v_mfma_f32_16x16x32_bf16 v[36:39], v[170:173], v[178:181], v[36:39]
	v_mfma_f32_16x16x32_bf16 v[28:31], v[162:165], v[186:189], v[28:31]
	v_mfma_f32_16x16x32_bf16 v[24:27], v[170:173], v[186:189], v[24:27]
	v_mfma_f32_16x16x32_bf16 v[16:19], v[162:165], v[194:197], v[16:19]
	v_mfma_f32_16x16x32_bf16 v[12:15], v[170:173], v[194:197], v[12:15]
	v_mfma_f32_16x16x32_bf16 v[4:7], v[162:165], v[202:205], v[4:7]
	v_mfma_f32_16x16x32_bf16 v[0:3], v[170:173], v[202:205], v[0:3]
	v_mfma_f32_16x16x32_bf16 v[40:43], v[166:169], v[182:185], v[40:43]
	v_mfma_f32_16x16x32_bf16 v[36:39], v[174:177], v[182:185], v[36:39]
	v_mfma_f32_16x16x32_bf16 v[28:31], v[166:169], v[190:193], v[28:31]
	v_mfma_f32_16x16x32_bf16 v[24:27], v[174:177], v[190:193], v[24:27]
	v_mfma_f32_16x16x32_bf16 v[16:19], v[166:169], v[198:201], v[16:19]
	v_mfma_f32_16x16x32_bf16 v[12:15], v[174:177], v[198:201], v[12:15]
	v_mfma_f32_16x16x32_bf16 v[4:7], v[166:169], v[206:209], v[4:7]
	v_mfma_f32_16x16x32_bf16 v[0:3], v[174:177], v[206:209], v[0:3]
	s_setprio 0
	s_barrier
	s_add_i32 s54, 0, 0x18000
	s_add_i32 s55, 0, 0x1c000
	v_add_u32_e32 v158, s54, v145
	v_add_u32_e32 v174, s55, v145
	ds_read_b128 v[138:141], v158
	ds_read_b128 v[150:153], v158 offset:1024
	ds_read_b128 v[154:157], v158 offset:2048
	ds_read_b128 v[158:161], v158 offset:3072
	ds_read_b128 v[162:165], v174
	ds_read_b128 v[166:169], v174 offset:1024
	ds_read_b128 v[170:173], v174 offset:2048
	ds_read_b128 v[174:177], v174 offset:3072
	s_add_u32 s26, s26, 0x40000
	s_addc_u32 s27, s27, 0
	s_mov_b32 m0, s35
	ds_read_b128 v[178:181], v149 offset:32768
	ds_read_b128 v[182:185], v149 offset:33792
	ds_read_b128 v[186:189], v149 offset:34816
	ds_read_b128 v[190:193], v149 offset:35840
	ds_read_b128 v[194:197], v149 offset:36864
	ds_read_b128 v[198:201], v149 offset:37888
	ds_read_b128 v[202:205], v149 offset:38912
	ds_read_b128 v[206:209], v149 offset:39936
	global_load_lds_dwordx4 v130, s[26:27]
	s_mov_b32 m0, s36
	s_nop 0
	global_load_lds_dwordx4 v128, s[26:27]
	s_waitcnt vmcnt(8)
	s_waitcnt lgkmcnt(0)
	s_barrier
	s_setprio 1
	s_waitcnt lgkmcnt(0)
	v_mfma_f32_16x16x32_bf16 v[124:127], v[138:141], v[178:181], v[124:127]
	v_mfma_f32_16x16x32_bf16 v[120:123], v[154:157], v[178:181], v[120:123]
	v_mfma_f32_16x16x32_bf16 v[116:119], v[138:141], v[186:189], v[116:119]
	v_mfma_f32_16x16x32_bf16 v[112:115], v[154:157], v[186:189], v[112:115]
	v_mfma_f32_16x16x32_bf16 v[104:107], v[138:141], v[194:197], v[104:107]
	v_mfma_f32_16x16x32_bf16 v[96:99], v[154:157], v[194:197], v[96:99]
	v_mfma_f32_16x16x32_bf16 v[88:91], v[138:141], v[202:205], v[88:91]
	v_mfma_f32_16x16x32_bf16 v[80:83], v[154:157], v[202:205], v[80:83]
	v_mfma_f32_16x16x32_bf16 v[124:127], v[150:153], v[182:185], v[124:127]
	v_mfma_f32_16x16x32_bf16 v[120:123], v[158:161], v[182:185], v[120:123]
	v_mfma_f32_16x16x32_bf16 v[116:119], v[150:153], v[190:193], v[116:119]
	v_mfma_f32_16x16x32_bf16 v[112:115], v[158:161], v[190:193], v[112:115]
	v_mfma_f32_16x16x32_bf16 v[104:107], v[150:153], v[198:201], v[104:107]
	v_mfma_f32_16x16x32_bf16 v[96:99], v[158:161], v[198:201], v[96:99]
	v_mfma_f32_16x16x32_bf16 v[88:91], v[150:153], v[206:209], v[88:91]
	v_mfma_f32_16x16x32_bf16 v[80:83], v[158:161], v[206:209], v[80:83]
	s_setprio 0
	s_setprio 1
	v_mfma_f32_16x16x32_bf16 v[108:111], v[162:165], v[178:181], v[108:111]
	v_mfma_f32_16x16x32_bf16 v[100:103], v[170:173], v[178:181], v[100:103]
	v_mfma_f32_16x16x32_bf16 v[92:95], v[162:165], v[186:189], v[92:95]
	v_mfma_f32_16x16x32_bf16 v[84:87], v[170:173], v[186:189], v[84:87]
	v_mfma_f32_16x16x32_bf16 v[76:79], v[162:165], v[194:197], v[76:79]
	v_mfma_f32_16x16x32_bf16 v[72:75], v[170:173], v[194:197], v[72:75]
	v_mfma_f32_16x16x32_bf16 v[68:71], v[162:165], v[202:205], v[68:71]
	v_mfma_f32_16x16x32_bf16 v[64:67], v[170:173], v[202:205], v[64:67]
	v_mfma_f32_16x16x32_bf16 v[108:111], v[166:169], v[182:185], v[108:111]
	v_mfma_f32_16x16x32_bf16 v[100:103], v[174:177], v[182:185], v[100:103]
	v_mfma_f32_16x16x32_bf16 v[92:95], v[166:169], v[190:193], v[92:95]
	v_mfma_f32_16x16x32_bf16 v[84:87], v[174:177], v[190:193], v[84:87]
	v_mfma_f32_16x16x32_bf16 v[76:79], v[166:169], v[198:201], v[76:79]
	v_mfma_f32_16x16x32_bf16 v[72:75], v[174:177], v[198:201], v[72:75]
	v_mfma_f32_16x16x32_bf16 v[68:71], v[166:169], v[206:209], v[68:71]
	v_mfma_f32_16x16x32_bf16 v[64:67], v[174:177], v[206:209], v[64:67]
	s_setprio 0
	s_barrier
	s_add_i32 s26, s54, s29
	s_add_i32 m0, s26, 0xffffff80
	ds_read_b128 v[178:181], v149 offset:49152
	ds_read_b128 v[182:185], v149 offset:50176
	ds_read_b128 v[186:189], v149 offset:51200
	ds_read_b128 v[190:193], v149 offset:52224
	ds_read_b128 v[194:197], v149 offset:53248
	ds_read_b128 v[198:201], v149 offset:54272
	ds_read_b128 v[202:205], v149 offset:55296
	ds_read_b128 v[206:209], v149 offset:56320
	global_load_lds_dwordx4 v130, s[24:25] offset:128
	s_add_i32 m0, s26, 0x1f80
	s_add_i32 s26, s55, s29
	global_load_lds_dwordx4 v128, s[24:25] offset:128
	s_add_u32 s24, s24, 0x40080
	s_addc_u32 s25, s25, 0
	s_mov_b32 m0, s26
	s_nop 0
	global_load_lds_dwordx4 v130, s[24:25]
	s_add_i32 m0, s26, 0x2000
	s_nop 0
	global_load_lds_dwordx4 v128, s[24:25]
	v_lshl_add_u64 v[142:143], v[212:213], 0, s[8:9]
	s_mov_b32 m0, s38
	s_nop 0
	global_load_lds_dwordx4 v[142:143], off
	v_lshl_add_u64 v[142:143], v[214:215], 0, s[8:9]
	s_mov_b32 m0, s39
	s_nop 0
	global_load_lds_dwordx4 v[142:143], off
	s_waitcnt vmcnt(8)
	s_waitcnt lgkmcnt(0)
	s_barrier
	s_setprio 1
	s_waitcnt lgkmcnt(0)
	v_mfma_f32_16x16x32_bf16 v[60:63], v[138:141], v[178:181], v[60:63]
	v_mfma_f32_16x16x32_bf16 v[56:59], v[154:157], v[178:181], v[56:59]
	v_mfma_f32_16x16x32_bf16 v[52:55], v[138:141], v[186:189], v[52:55]
	v_mfma_f32_16x16x32_bf16 v[48:51], v[154:157], v[186:189], v[48:51]
	v_mfma_f32_16x16x32_bf16 v[44:47], v[138:141], v[194:197], v[44:47]
	v_mfma_f32_16x16x32_bf16 v[32:35], v[154:157], v[194:197], v[32:35]
	v_mfma_f32_16x16x32_bf16 v[20:23], v[138:141], v[202:205], v[20:23]
	v_mfma_f32_16x16x32_bf16 v[8:11], v[154:157], v[202:205], v[8:11]
	v_mfma_f32_16x16x32_bf16 v[60:63], v[150:153], v[182:185], v[60:63]
	v_mfma_f32_16x16x32_bf16 v[56:59], v[158:161], v[182:185], v[56:59]
	v_mfma_f32_16x16x32_bf16 v[52:55], v[150:153], v[190:193], v[52:55]
	v_mfma_f32_16x16x32_bf16 v[48:51], v[158:161], v[190:193], v[48:51]
	v_mfma_f32_16x16x32_bf16 v[44:47], v[150:153], v[198:201], v[44:47]
	v_mfma_f32_16x16x32_bf16 v[32:35], v[158:161], v[198:201], v[32:35]
	v_mfma_f32_16x16x32_bf16 v[20:23], v[150:153], v[206:209], v[20:23]
	v_mfma_f32_16x16x32_bf16 v[8:11], v[158:161], v[206:209], v[8:11]
	s_setprio 0
	s_setprio 1
	v_mfma_f32_16x16x32_bf16 v[40:43], v[162:165], v[178:181], v[40:43]
	v_mfma_f32_16x16x32_bf16 v[36:39], v[170:173], v[178:181], v[36:39]
	v_mfma_f32_16x16x32_bf16 v[28:31], v[162:165], v[186:189], v[28:31]
	v_mfma_f32_16x16x32_bf16 v[24:27], v[170:173], v[186:189], v[24:27]
	v_mfma_f32_16x16x32_bf16 v[16:19], v[162:165], v[194:197], v[16:19]
	v_mfma_f32_16x16x32_bf16 v[12:15], v[170:173], v[194:197], v[12:15]
	v_mfma_f32_16x16x32_bf16 v[4:7], v[162:165], v[202:205], v[4:7]
	v_mfma_f32_16x16x32_bf16 v[0:3], v[170:173], v[202:205], v[0:3]
	v_mfma_f32_16x16x32_bf16 v[40:43], v[166:169], v[182:185], v[40:43]
	v_mfma_f32_16x16x32_bf16 v[36:39], v[174:177], v[182:185], v[36:39]
	v_mfma_f32_16x16x32_bf16 v[28:31], v[166:169], v[190:193], v[28:31]
	v_mfma_f32_16x16x32_bf16 v[24:27], v[174:177], v[190:193], v[24:27]
	v_mfma_f32_16x16x32_bf16 v[16:19], v[166:169], v[198:201], v[16:19]
	v_mfma_f32_16x16x32_bf16 v[12:15], v[174:177], v[198:201], v[12:15]
	v_mfma_f32_16x16x32_bf16 v[4:7], v[166:169], v[206:209], v[4:7]
	v_mfma_f32_16x16x32_bf16 v[0:3], v[174:177], v[206:209], v[0:3]
	s_setprio 0
	s_barrier
	s_add_i32 s53, s53, 2
	s_add_u32 s2, s2, 0x100
	s_addc_u32 s3, s3, 0
	s_add_u32 s51, s51, 0x100
	s_addc_u32 s52, s52, 0
	s_cmp_gt_u32 s53, 13
	s_cbranch_scc0 .LBB0_1381
	s_and_b64 vcc, exec, s[10:11]
	s_cbranch_vccz .LBB0_1384
	s_barrier
